# EpiGlu: second-half residual prefetch as 4 dwordx4 loads (64-byte merged segments, permlane16_swap un-shuffle)
# speedup vs baseline: 1.0069x; 1.0005x over previous
.LBB0_1529:
	s_mov_b32 s0, s40
	s_lshl_b32 s1, s22, 7
	v_mov_b32_e32 v154, v182
	v_mov_b32_e32 v160, v183
	s_or_b32 s1, s1, s48
	s_lshl_b32 s0, s0, 8
	v_lshl_add_u32 v152, v160, 2, s1
	v_ashrrev_i32_e32 v153, 31, v152
	v_lshlrev_b64 v[80:81], 2, v[152:153]
	v_lshl_add_u64 v[82:83], s[12:13], 0, v[80:81]
	v_lshl_add_u64 v[84:85], s[26:27], 0, v[80:81]
	global_load_dwordx4 v[100:103], v[84:85], off
	global_load_dwordx4 v[92:95], v[82:83], off
	s_nop 0
	global_load_dwordx4 v[80:83], v[82:83], off offset:256
	s_nop 0
	global_load_dwordx4 v[84:87], v[84:85], off offset:256
	s_add_i32 s0, s0, s45
	v_add_u32_e32 v156, s0, v154
	v_lshlrev_b64 v[190:191], 1, v[152:153]
	v_ashrrev_i32_e32 v157, 31, v156
	v_lshl_add_u64 v[154:155], s[16:17], 0, v[190:191]
	v_lshlrev_b64 v[192:193], 12, v[156:157]
	v_lshl_add_u64 v[158:159], v[154:155], 0, v[192:193]
	v_mbcnt_lo_u32_b32 v214, -1, 0
	v_mbcnt_hi_u32_b32 v214, -1, v214
	v_lshrrev_b32_e32 v214, 4, v214
	v_and_b32_e32 v214, 1, v214
	v_mul_u32_u24_e32 v214, 0x78, v214
	v_mov_b32_e32 v215, 0
	global_load_dwordx2 v[194:195], v[158:159], off
	global_load_dwordx2 v[196:197], v[158:159], off offset:128
	v_add_u32_e32 v172, 16, v156
	v_add_u32_e32 v166, 32, v156
	v_add_u32_e32 v158, 48, v156
	v_ashrrev_i32_e32 v173, 31, v172
	v_ashrrev_i32_e32 v167, 31, v166
	v_ashrrev_i32_e32 v159, 31, v158
	v_lshlrev_b64 v[176:177], 12, v[172:173]
	v_lshlrev_b64 v[168:169], 12, v[166:167]
	v_cmp_eq_u32_e32 vcc, 0, v160
	v_lshlrev_b64 v[160:161], 12, v[158:159]
	v_lshl_add_u64 v[162:163], v[154:155], 0, v[176:177]
	v_lshl_add_u64 v[164:165], v[154:155], 0, v[168:169]
	v_lshl_add_u64 v[198:199], v[154:155], 0, v[160:161]
	global_load_dwordx2 v[180:181], v[162:163], off
	global_load_dwordx2 v[178:179], v[162:163], off offset:128
	global_load_dwordx2 v[174:175], v[164:165], off
	global_load_dwordx2 v[170:171], v[164:165], off offset:128
	s_nop 0
	global_load_dwordx2 v[164:165], v[198:199], off
	global_load_dwordx2 v[162:163], v[198:199], off offset:128
	v_add_u32_e32 v216, 0x80, v156
	v_ashrrev_i32_e32 v217, 31, v216
	v_lshlrev_b64 v[216:217], 12, v[216:217]
	v_lshl_add_u64 v[216:217], v[154:155], 0, v[216:217]
	v_add_u32_e32 v218, 0x90, v156
	v_ashrrev_i32_e32 v219, 31, v218
	v_lshlrev_b64 v[218:219], 12, v[218:219]
	v_lshl_add_u64 v[218:219], v[154:155], 0, v[218:219]
	v_add_u32_e32 v220, 0xa0, v156
	v_ashrrev_i32_e32 v221, 31, v220
	v_lshlrev_b64 v[220:221], 12, v[220:221]
	v_lshl_add_u64 v[220:221], v[154:155], 0, v[220:221]
	v_add_u32_e32 v240, 0xb0, v156
	v_ashrrev_i32_e32 v241, 31, v240
	v_lshlrev_b64 v[240:241], 12, v[240:241]
	v_lshl_add_u64 v[240:241], v[154:155], 0, v[240:241]
	v_lshl_add_u64 v[216:217], v[216:217], 0, v[214:215]
	global_load_dwordx4 v[224:227], v[216:217], off
	v_lshl_add_u64 v[218:219], v[218:219], 0, v[214:215]
	global_load_dwordx4 v[228:231], v[218:219], off
	v_lshl_add_u64 v[220:221], v[220:221], 0, v[214:215]
	global_load_dwordx4 v[232:235], v[220:221], off
	v_lshl_add_u64 v[240:241], v[240:241], 0, v[214:215]
	global_load_dwordx4 v[236:239], v[240:241], off
	s_lshl_b32 s0, s22, 2
	s_ashr_i32 s1, s0, 31
	s_waitcnt vmcnt(4)
	v_add_f32_e32 v141, v141, v101
	v_add_f32_e32 v143, v143, v103
	v_add_f32_e32 v140, v140, v100
	v_add_f32_e32 v142, v142, v102
	v_add_f32_e32 v132, v132, v84
	v_mul_f32_e32 v141, 0xbfb8aa3b, v141
	v_mul_f32_e32 v143, 0xbfb8aa3b, v143
	v_mul_f32_e32 v140, 0xbfb8aa3b, v140
	v_mul_f32_e32 v142, 0xbfb8aa3b, v142
	v_mul_f32_e32 v132, 0xbfb8aa3b, v132
	v_exp_f32_e32 v141, v141
	v_exp_f32_e32 v143, v143
	v_exp_f32_e32 v140, v140
	v_exp_f32_e32 v142, v142
	v_exp_f32_e32 v132, v132
	v_add_f32_e32 v141, 1.0, v141
	v_add_f32_e32 v143, 1.0, v143
	v_add_f32_e32 v140, 1.0, v140
	v_add_f32_e32 v142, 1.0, v142
	v_add_f32_e32 v132, 1.0, v132
	v_rcp_f32_e32 v141, v141
	v_rcp_f32_e32 v143, v143
	v_add_f32_e32 v133, v133, v85
	v_rcp_f32_e32 v140, v140
	v_rcp_f32_e32 v142, v142
	v_rcp_f32_e32 v132, v132
	v_mul_f32_e32 v133, 0xbfb8aa3b, v133
	v_add_f32_e32 v137, v137, v93
	v_add_f32_e32 v139, v139, v95
	v_lshlrev_b32_e32 v189, 16, v194
	v_and_b32_e32 v194, 0xffff0000, v194
	v_lshlrev_b32_e32 v198, 16, v195
	v_and_b32_e32 v195, 0xffff0000, v195
	v_exp_f32_e32 v133, v133
	v_add_f32_e32 v136, v136, v92
	v_add_f32_e32 v138, v138, v94
	v_add_f32_e32 v128, v128, v80
	v_lshlrev_b32_e32 v199, 16, v196
	v_fmac_f32_e32 v194, v137, v141
	v_fmac_f32_e32 v195, v139, v143
	v_fmac_f32_e32 v189, v136, v140
	v_fmac_f32_e32 v198, v138, v142
	v_fmac_f32_e32 v199, v128, v132
	v_mul_f32_e32 v128, v194, v194
	v_mul_f32_e32 v132, v195, v195
	v_add_f32_e32 v134, v134, v86
	v_fmac_f32_e32 v128, v189, v189
	v_fmac_f32_e32 v132, v198, v198
	v_add_f32_e32 v133, 1.0, v133
	v_add_f32_e32 v128, v128, v132
	v_mul_f32_e32 v132, 0xbfb8aa3b, v134
	v_add_f32_e32 v134, v135, v87
	v_rcp_f32_e32 v133, v133
	v_exp_f32_e32 v132, v132
	v_mul_f32_e32 v134, 0xbfb8aa3b, v134
	v_exp_f32_e32 v134, v134
	v_add_f32_e32 v129, v129, v81
	v_and_b32_e32 v196, 0xffff0000, v196
	v_fmac_f32_e32 v196, v129, v133
	v_add_f32_e32 v129, 1.0, v132
	v_rcp_f32_e32 v129, v129
	v_add_f32_e32 v132, 1.0, v134
	v_rcp_f32_e32 v132, v132
	v_lshlrev_b32_e32 v200, 16, v197
	v_add_f32_e32 v130, v130, v82
	v_and_b32_e32 v197, 0xffff0000, v197
	v_fmac_f32_e32 v200, v130, v129
	v_add_f32_e32 v129, v131, v83
	v_fmac_f32_e32 v197, v129, v132
	v_mul_f32_e32 v129, v196, v196
	v_mul_f32_e32 v130, v197, v197
	v_fmac_f32_e32 v129, v199, v199
	v_fmac_f32_e32 v130, v200, v200
	v_add_f32_e32 v129, v129, v130
	v_and_b32_e32 v130, 64, v188
	v_add_f32_e32 v129, v128, v129
	v_xor_b32_e32 v128, 16, v188
	v_add_u32_e32 v136, 64, v130
	v_cmp_lt_i32_e64 s[2:3], v128, v136
	v_lshl_add_u64 v[130:131], s[16:17], 0, v[192:193]
	v_lshl_add_u64 v[134:135], v[130:131], 0, v[190:191]
	v_cndmask_b32_e64 v128, v188, v128, s[2:3]
	v_lshlrev_b32_e32 v128, 2, v128
	v_mov_b32_e32 v137, v129
	s_nop 1
	v_permlane16_swap_b32_e32 v137, v129
	v_cvt_pk_bf16_f32 v132, v189, v194
	v_cvt_pk_bf16_f32 v133, v198, v195
	v_mov_b32_e32 v204, v132
	v_mov_b32_e32 v205, v133
	v_cvt_pk_bf16_f32 v132, v199, v196
	s_waitcnt lgkmcnt(0)
	v_add_f32_e32 v130, v129, v137
	v_xor_b32_e32 v129, 32, v188
	v_cmp_lt_i32_e64 s[2:3], v129, v136
	v_cvt_pk_bf16_f32 v133, v200, v197
	v_mov_b32_e32 v206, v132
	v_mov_b32_e32 v207, v133
	v_lshl_add_u64 v[212:213], v[134:135], 0, v[214:215]
	s_nop 0
	v_permlane16_swap_b32_e32 v204, v206
	v_permlane16_swap_b32_e32 v205, v207
	global_store_dwordx4 v[212:213], v[204:207], off
	s_nop 0
	v_cndmask_b32_e64 v129, v188, v129, s[2:3]
	v_lshlrev_b32_e32 v129, 2, v129
	v_mov_b32_e32 v131, v130
	s_nop 1
	v_permlane32_swap_b32_e32 v131, v130
	s_and_saveexec_b64 s[2:3], vcc
	s_cbranch_execz .LBB0_1531
	s_waitcnt lgkmcnt(0)
	v_add_f32_e32 v132, v130, v131
	v_lshlrev_b64 v[130:131], 8, v[156:157]
	v_lshl_add_u64 v[130:131], s[18:19], 0, v[130:131]
	v_lshl_add_u64 v[130:131], s[0:1], 2, v[130:131]
	s_lshl_b32 s22, s44, 2
	v_lshl_add_u64 v[130:131], v[130:131], 0, s[22:23]
	global_store_dword v[130:131], v132, off

.LBB0_1537:
	s_or_b64 exec, exec, s[2:3]
	v_add_u32_e32 v78, 0x80, v156
	v_ashrrev_i32_e32 v79, 31, v78
	v_lshlrev_b64 v[90:91], 12, v[78:79]
	s_waitcnt lgkmcnt(0)
	v_lshl_add_u64 v[64:65], v[154:155], 0, v[90:91]
	s_waitcnt vmcnt(8)
	v_permlane16_swap_b32_e32 v224, v226
	v_permlane16_swap_b32_e32 v225, v227
	v_permlane16_swap_b32_e32 v228, v230
	v_permlane16_swap_b32_e32 v229, v231
	v_permlane16_swap_b32_e32 v232, v234
	v_permlane16_swap_b32_e32 v233, v235
	v_permlane16_swap_b32_e32 v236, v238
	v_permlane16_swap_b32_e32 v237, v239
	v_mov_b32_e32 v96, v224
	v_mov_b32_e32 v97, v225
	v_mov_b32_e32 v98, v226
	v_mov_b32_e32 v99, v227
	v_add_u32_e32 v70, 0x90, v156
	v_add_u32_e32 v66, 0xa0, v156
	v_add_u32_e32 v64, 0xb0, v156
	v_ashrrev_i32_e32 v71, 31, v70
	v_ashrrev_i32_e32 v67, 31, v66
	v_add_f32_e32 v110, v62, v102
	v_add_f32_e32 v112, v63, v103
	v_ashrrev_i32_e32 v65, 31, v64
	v_lshlrev_b64 v[74:75], 12, v[70:71]
	v_lshlrev_b64 v[62:63], 12, v[66:67]
	v_add_f32_e32 v106, v60, v100
	v_add_f32_e32 v107, v56, v92
	v_add_f32_e32 v108, v61, v101
	v_add_f32_e32 v109, v57, v93
	v_add_f32_e32 v111, v58, v94
	v_add_f32_e32 v113, v59, v95
	v_lshlrev_b64 v[56:57], 12, v[64:65]
	v_lshl_add_u64 v[58:59], v[154:155], 0, v[74:75]
	v_lshl_add_u64 v[60:61], v[154:155], 0, v[62:63]
	v_lshl_add_u64 v[104:105], v[154:155], 0, v[56:57]
	v_mov_b32_e32 v88, v228
	v_mov_b32_e32 v89, v229
	v_mov_b32_e32 v76, v230
	v_mov_b32_e32 v77, v231
	v_mov_b32_e32 v72, v232
	v_mov_b32_e32 v73, v233
	v_mov_b32_e32 v68, v234
	v_mov_b32_e32 v69, v235
	s_nop 0
	v_mov_b32_e32 v60, v236
	v_mov_b32_e32 v61, v237
	v_mov_b32_e32 v58, v238
	v_mov_b32_e32 v59, v239
	v_add_f32_e32 v52, v52, v84
	v_add_f32_e32 v53, v53, v85
	v_mul_f32_e32 v105, 0xbfb8aa3b, v108
	v_mul_f32_e32 v108, 0xbfb8aa3b, v112
	v_mul_f32_e32 v104, 0xbfb8aa3b, v106
	v_mul_f32_e32 v106, 0xbfb8aa3b, v110
	v_mul_f32_e32 v52, 0xbfb8aa3b, v52
	v_mul_f32_e32 v53, 0xbfb8aa3b, v53
	v_exp_f32_e32 v105, v105
	v_exp_f32_e32 v108, v108
	v_exp_f32_e32 v104, v104
	v_exp_f32_e32 v106, v106
	v_exp_f32_e32 v52, v52
	v_exp_f32_e32 v53, v53
	v_add_f32_e32 v105, 1.0, v105
	v_add_f32_e32 v108, 1.0, v108
	v_add_f32_e32 v54, v54, v86
	v_add_f32_e32 v104, 1.0, v104
	v_add_f32_e32 v106, 1.0, v106
	v_add_f32_e32 v52, 1.0, v52
	v_add_f32_e32 v53, 1.0, v53
	v_rcp_f32_e32 v105, v105
	v_rcp_f32_e32 v108, v108
	v_add_f32_e32 v55, v55, v87
	v_mul_f32_e32 v54, 0xbfb8aa3b, v54
	v_rcp_f32_e32 v104, v104
	v_rcp_f32_e32 v106, v106
	v_rcp_f32_e32 v52, v52
	v_rcp_f32_e32 v53, v53
	v_mul_f32_e32 v55, 0xbfb8aa3b, v55
	v_exp_f32_e32 v54, v54
	v_exp_f32_e32 v55, v55
	v_add_f32_e32 v48, v48, v80
	v_add_f32_e32 v49, v49, v81
	v_add_f32_e32 v54, 1.0, v54
	v_rcp_f32_e32 v54, v54
	v_add_f32_e32 v50, v50, v82
	v_lshlrev_b32_e32 v110, 16, v96
	v_and_b32_e32 v96, 0xffff0000, v96
	v_lshlrev_b32_e32 v112, 16, v97
	v_and_b32_e32 v97, 0xffff0000, v97
	v_lshlrev_b32_e32 v114, 16, v98
	v_and_b32_e32 v98, 0xffff0000, v98
	v_fmac_f32_e32 v96, v109, v105
	v_fmac_f32_e32 v97, v113, v108
	v_fmac_f32_e32 v110, v107, v104
	v_fmac_f32_e32 v112, v111, v106
	v_fmac_f32_e32 v114, v48, v52
	v_fmac_f32_e32 v98, v49, v53
	v_mul_f32_e32 v48, v96, v96
	v_mul_f32_e32 v49, v97, v97
	v_fmac_f32_e32 v48, v110, v110
	v_fmac_f32_e32 v49, v112, v112
	v_add_f32_e32 v48, v48, v49
	v_add_f32_e32 v49, 1.0, v55
	v_rcp_f32_e32 v49, v49
	v_lshlrev_b32_e32 v115, 16, v99
	v_and_b32_e32 v99, 0xffff0000, v99
	v_fmac_f32_e32 v115, v50, v54
	v_add_f32_e32 v50, v51, v83
	v_fmac_f32_e32 v99, v50, v49
	v_mul_f32_e32 v49, v98, v98
	v_mul_f32_e32 v50, v99, v99
	v_fmac_f32_e32 v49, v114, v114
	v_fmac_f32_e32 v50, v115, v115
	v_add_f32_e32 v49, v49, v50
	v_add_f32_e32 v54, v48, v49
	v_mov_b32_e32 v55, v54
	s_nop 1
	v_permlane16_swap_b32_e32 v55, v54
	v_lshl_add_u64 v[48:49], s[16:17], 0, v[90:91]
	v_lshl_add_u64 v[52:53], v[152:153], 1, v[48:49]
	v_cvt_pk_bf16_f32 v50, v110, v96
	v_cvt_pk_bf16_f32 v51, v112, v97
	s_waitcnt lgkmcnt(0)
	v_add_f32_e32 v48, v54, v55
	v_mov_b32_e32 v49, v48
	s_nop 1
	v_permlane32_swap_b32_e32 v49, v48
	v_mov_b32_e32 v204, v50
	v_mov_b32_e32 v205, v51
	v_cvt_pk_bf16_f32 v50, v114, v98
	v_cvt_pk_bf16_f32 v51, v115, v99
	v_mov_b32_e32 v206, v50
	v_mov_b32_e32 v207, v51
	v_lshl_add_u64 v[212:213], v[52:53], 0, v[214:215]
	s_nop 0
	v_permlane16_swap_b32_e32 v204, v206
	v_permlane16_swap_b32_e32 v205, v207
	global_store_dwordx4 v[212:213], v[204:207], off
	s_and_saveexec_b64 s[2:3], vcc
	s_cbranch_execz .LBB0_1539
	s_waitcnt lgkmcnt(0)
	v_add_f32_e32 v50, v48, v49
	v_lshlrev_b64 v[48:49], 8, v[78:79]
	v_lshl_add_u64 v[48:49], s[18:19], 0, v[48:49]
	v_lshl_add_u64 v[48:49], s[0:1], 2, v[48:49]
	s_lshl_b32 s22, s44, 2
	v_lshl_add_u64 v[48:49], v[48:49], 0, s[22:23]
	global_store_dword v[48:49], v50, off
